# v18 + dilated softmax algebra: scores kept unscaled (p + |d|*(-8 slope)), scale folded into the exp2 argument fma; 48 fewer VALU multiplies per unit
# speedup vs baseline: 1.0116x; 1.0002x over previous
; DI void unit(const bf16* __restrict__ QKV, const int* __restrict__ pos, bf16* __restrict__ OA, float* __restrict__ LSE,
;              int b, int h, int d, int r, int qb, float slope, char* lds) {
;     ...
;       for (int j = 0; j < 4; ++j) { const int rr = 4 * g + j, kr = j + 8 * g + 4 * hi;
;         float sc = fmaf(__builtin_fabsf(pqf - pk4[j]), -sl2, p[ta][rr] * C);
;         if (ta == 0) sc = (kr >= r32) ? sc : -1e30f;
;         if (ta == 4) sc = (kr <= r32) ? sc : -1e30f;
; __global__ void __launch_bounds__(512, 2) fwd_megakernel(Params P) {
;     ...
;         if (PH(18)) for (int u = bid; u < 3072; u += G) {
;             const int br = u >> 10, v = u & 1023, h = v & 7, w = v >> 3;
;             const int b = w >> 4, blk = w & 15;
;             int d, r, qb; if (br == 0) { d = 1; r = 0; qb = blk; } else if (br == 1) { d = 4; r = blk & 3; qb = blk >> 2; } else { d = 16; r = blk; qb = 0; }
;             const float slope = __builtin_exp2f(-(float)(h + 1));
.Ldil_noprio:
	s_cmpk_gt_i32 s33, 0xbff
	s_cbranch_scc1 .Ldil_done
	s_add_u32 s0, s26, 0x9c00000
	s_addc_u32 s1, s27, 0
	s_add_u32 s10, s26, 0xfc00000
	s_addc_u32 s11, s27, 0
	s_add_u32 s13, s26, 0x7400000
	s_addc_u32 s38, s27, 0
	s_mov_b32 s9, 0
	s_load_dwordx2 s[40:41], s[98:99], 0x10
	s_movk_i32 s39, 0x70
	s_movk_i32 s42, 0x180
	v_mov_b32_e32 v93, 0
	s_mov_b32 s43, 0x42fc0000
	s_movk_i32 s44, 0x60
	s_mov_b32 s45, 0xf149f2ca
	v_mov_b32_e32 v96, 0x42800000
	s_add_i32 s46, 0, 0x18000
	v_mov_b32_e32 v97, 0xf149f2ca
	v_lshrrev_b32_e32 v234, 3, v242
	v_lshlrev_b32_e32 v235, 4, v242
	v_and_b32_e32 v235, 0x70, v235
	v_lshrrev_b32_e32 v222, 1, v234
	v_and_b32_e32 v222, 7, v222
	v_lshlrev_b32_e32 v222, 4, v222
	v_xor_b32_e32 v222, v222, v235
	v_lshl_or_b32 v222, v234, 7, v222
	v_and_b32_e32 v223, 51, v234
	v_and_b32_e32 v224, 4, v234
	v_lshlrev_b32_e32 v224, 1, v224
	v_or_b32_e32 v223, v223, v224
	v_and_b32_e32 v224, 8, v234
	v_lshrrev_b32_e32 v224, 1, v224
	v_or_b32_e32 v223, v223, v224
	v_lshrrev_b32_e32 v224, 3, v223
	v_lshlrev_b32_e32 v224, 1, v224
	v_bfe_u32 v225, v242, 2, 1
	v_add_u32_e32 v224, v224, v225
	v_lshlrev_b32_e32 v224, 9, v224
	v_and_b32_e32 v225, 7, v223
	v_lshlrev_b32_e32 v225, 5, v225
	v_and_b32_e32 v226, 3, v242
	v_lshl_or_b32 v225, v226, 3, v225
	v_lshlrev_b32_e32 v225, 1, v225
	v_add_u32_e32 v223, v224, v225
	v_add_u32_e32 v223, 0xc000, v223
	v_and_b32_e32 v236, 31, v242
	v_bfe_u32 v237, v242, 5, 1
	v_lshlrev_b32_e32 v237, 2, v237
	v_mov_b32_e32 v238, 0xf149f2ca
	v_mov_b32_e32 v240, 0
	v_add_u32_e32 v239, 0, v237
	v_cmp_ge_u32_e32 vcc, v239, v236
	s_nop 1
	v_cndmask_b32_e32 v134, v238, v240, vcc
	v_add_u32_e32 v239, 1, v237
	v_cmp_ge_u32_e32 vcc, v239, v236
	s_nop 1
	v_cndmask_b32_e32 v135, v238, v240, vcc
	v_add_u32_e32 v239, 2, v237
	v_cmp_ge_u32_e32 vcc, v239, v236
	s_nop 1
	v_cndmask_b32_e32 v136, v238, v240, vcc
	v_add_u32_e32 v239, 3, v237
	v_cmp_ge_u32_e32 vcc, v239, v236
	s_nop 1
	v_cndmask_b32_e32 v137, v238, v240, vcc
	v_add_u32_e32 v239, 8, v237
	v_cmp_ge_u32_e32 vcc, v239, v236
	s_nop 1
	v_cndmask_b32_e32 v138, v238, v240, vcc
	v_add_u32_e32 v239, 9, v237
	v_cmp_ge_u32_e32 vcc, v239, v236
	s_nop 1
	v_cndmask_b32_e32 v139, v238, v240, vcc
	v_add_u32_e32 v239, 10, v237
	v_cmp_ge_u32_e32 vcc, v239, v236
	s_nop 1
	v_cndmask_b32_e32 v140, v238, v240, vcc
	v_add_u32_e32 v239, 11, v237
	v_cmp_ge_u32_e32 vcc, v239, v236
	s_nop 1
	v_cndmask_b32_e32 v141, v238, v240, vcc
	v_add_u32_e32 v239, 16, v237
	v_cmp_ge_u32_e32 vcc, v239, v236
	s_nop 1
	v_cndmask_b32_e32 v142, v238, v240, vcc
	v_add_u32_e32 v239, 17, v237
	v_cmp_ge_u32_e32 vcc, v239, v236
	s_nop 1
	v_cndmask_b32_e32 v143, v238, v240, vcc
	v_add_u32_e32 v239, 18, v237
	v_cmp_ge_u32_e32 vcc, v239, v236
	s_nop 1
	v_cndmask_b32_e32 v144, v238, v240, vcc
	v_add_u32_e32 v239, 19, v237
	v_cmp_ge_u32_e32 vcc, v239, v236
	s_nop 1
	v_cndmask_b32_e32 v145, v238, v240, vcc
	v_add_u32_e32 v239, 24, v237
	v_cmp_ge_u32_e32 vcc, v239, v236
	s_nop 1
	v_cndmask_b32_e32 v148, v238, v240, vcc
	v_add_u32_e32 v239, 25, v237
	v_cmp_ge_u32_e32 vcc, v239, v236
	s_nop 1
	v_cndmask_b32_e32 v149, v238, v240, vcc
	v_add_u32_e32 v239, 26, v237
	v_cmp_ge_u32_e32 vcc, v239, v236
	s_nop 1
	v_cndmask_b32_e32 v150, v238, v240, vcc
	v_add_u32_e32 v239, 27, v237
	v_cmp_ge_u32_e32 vcc, v239, v236
	s_nop 1
	v_cndmask_b32_e32 v152, v238, v240, vcc
	v_add_u32_e32 v239, 0, v237
	v_cmp_le_u32_e32 vcc, v239, v236
	s_nop 1
	v_cndmask_b32_e32 v153, v238, v240, vcc
	v_add_u32_e32 v239, 1, v237
	v_cmp_le_u32_e32 vcc, v239, v236
	s_nop 1
	v_cndmask_b32_e32 v154, v238, v240, vcc
	v_add_u32_e32 v239, 2, v237
	v_cmp_le_u32_e32 vcc, v239, v236
	s_nop 1
	v_cndmask_b32_e32 v155, v238, v240, vcc
	v_add_u32_e32 v239, 3, v237
	v_cmp_le_u32_e32 vcc, v239, v236
	s_nop 1
	v_cndmask_b32_e32 v156, v238, v240, vcc
	v_add_u32_e32 v239, 8, v237
	v_cmp_le_u32_e32 vcc, v239, v236
	s_nop 1
	v_cndmask_b32_e32 v157, v238, v240, vcc
	v_add_u32_e32 v239, 9, v237
	v_cmp_le_u32_e32 vcc, v239, v236
	s_nop 1
	v_cndmask_b32_e32 v158, v238, v240, vcc
	v_add_u32_e32 v239, 10, v237
	v_cmp_le_u32_e32 vcc, v239, v236
	s_nop 1
	v_cndmask_b32_e32 v159, v238, v240, vcc
	v_add_u32_e32 v239, 11, v237
	v_cmp_le_u32_e32 vcc, v239, v236
	s_nop 1
	v_cndmask_b32_e32 v162, v238, v240, vcc
	v_add_u32_e32 v239, 16, v237
	v_cmp_le_u32_e32 vcc, v239, v236
	s_nop 1
	v_cndmask_b32_e32 v163, v238, v240, vcc
	v_add_u32_e32 v239, 17, v237
	v_cmp_le_u32_e32 vcc, v239, v236
	s_nop 1
	v_cndmask_b32_e32 v212, v238, v240, vcc
	v_add_u32_e32 v239, 18, v237
	v_cmp_le_u32_e32 vcc, v239, v236
	s_nop 1
	v_cndmask_b32_e32 v228, v238, v240, vcc
	v_add_u32_e32 v239, 19, v237
	v_cmp_le_u32_e32 vcc, v239, v236
	s_nop 1
	v_cndmask_b32_e32 v229, v238, v240, vcc
	v_add_u32_e32 v239, 24, v237
	v_cmp_le_u32_e32 vcc, v239, v236
	s_nop 1
	v_cndmask_b32_e32 v230, v238, v240, vcc
	v_add_u32_e32 v239, 25, v237
	v_cmp_le_u32_e32 vcc, v239, v236
	s_nop 1
	v_cndmask_b32_e32 v231, v238, v240, vcc
	v_add_u32_e32 v239, 26, v237
	v_cmp_le_u32_e32 vcc, v239, v236
	s_nop 1
	v_cndmask_b32_e32 v232, v238, v240, vcc
	v_add_u32_e32 v239, 27, v237
	v_cmp_le_u32_e32 vcc, v239, v236
	s_nop 1
	v_cndmask_b32_e32 v233, v238, v240, vcc
	s_waitcnt lgkmcnt(0)
	s_mov_b32 s76, 0x3e38aa3b
	s_mov_b32 s47, s33
	s_branch .LBB0_858

; __device__ __forceinline__ int opaque_tid() { int t = threadIdx.x; asm volatile("" : "+v"(t)); return t; }
; #define SBAR() __builtin_amdgcn_sched_barrier(0)
; DI int v_st64(int k, int c) { const int kk = (k & ~0xC) | ((k & 4) << 1) | ((k & 8) >> 1); return ((kk >> 3) * 2 + (c >> 5)) * 512 + ((kk & 7) * 32 + (c & 31)) * 2; }
; DI void unit(const bf16* __restrict__ QKV, const int* __restrict__ pos, bf16* __restrict__ OA, float* __restrict__ LSE,
;              int b, int h, int d, int r, int qb, float slope, char* lds) {
;   const int tid = opaque_tid(), wid = tid >> 6, lane = tid & 63, r32 = lane & 31, hi = lane >> 5;
;   const int L = SEQ / d, u0 = qb * 256;
;   char* K_lds = lds + OFF_K; char* V_lds = lds + OFF_V; int* posk = (int*)(lds + OFF_POS); float* ws = (float*)(lds + OFF_WS) + wid * 64;
;   const bf16* base = QKV + (size_t)(b * 8 + h) * SEQ * 64;
;   constexpr size_t PLANE = (size_t)NB * 8 * SEQ * 64 * 2;
;   auto stage = [&](const int i0) {
;     bf16x8 kreg[3], vreg[3];
; #pragma unroll
;     for (int i = 0; i < 3; ++i) { const int idx = tid + (i0 + i) * 512, row = idx >> 3, ch = idx & 7, v = u0 - 64 + row; const bool ok = (v >= 0) && (v < L);
;       const unsigned go = (unsigned)((r + d * (ok ? v : 0)) * 64 + ch * 8) * 2u;
;       kreg[i] = *(const bf16x8*)((const char*)base + PLANE + go); vreg[i] = *(const bf16x8*)((const char*)base + 2 * PLANE + go);
;       if (!ok) { kreg[i] = bf16x8{}; vreg[i] = bf16x8{}; } }
; #pragma unroll
;     for (int i = 0; i < 3; ++i) { const int idx = tid + (i0 + i) * 512, row = idx >> 3, ch = idx & 7;
;       *(bf16x8*)(K_lds + PSWZ(row, ch * 16)) = kreg[i]; *(bf16x8*)(V_lds + v_st64(row, ch * 8)) = vreg[i]; }
;   };
;   stage(0); SBAR(); stage(3); SBAR();
;   float pkv = 3.0e8f; if (tid < 384) { const int v = u0 - 64 + tid; if (v >= 0 && v < L) pkv = (float)pos[b * SEQ + r + d * v]; }
;   const int uq = u0 + wid * 32 + r32, tq = r + d * uq;
;   bf16x8 qr[4];
; #pragma unroll
;   for (int d0 = 0; d0 < 4; ++d0) qr[d0] = *(const bf16x8*)((const char*)base + (unsigned)(tq * 64 + d0 * 16 + hi * 8) * 2u);
;   const int pq = pos[b * SEQ + tq];
;   if (tid < 384) ((float*)posk)[tid] = pkv;
;   __syncthreads();
.LBB0_864:
	s_and_b32 s48, s47, 7
	s_bfe_u32 s30, s47, 0x30007
	s_ff1_i32_b32 s3, s8
	s_lshr_b32 s49, 0x1000, s3
	s_mov_b32 s77, s3
	s_lshl_b32 s31, s2, 8
	s_lshl_b32 s2, s48, 19
	s_lshl_b32 s3, s30, 22
	s_or_b32 s2, s3, s2
	s_add_u32 s16, s10, s2
	v_mov_b32_e32 v4, v242
	s_addc_u32 s17, s11, 0
	s_sub_i32 s50, s31, 64
	s_add_u32 s18, s16, 0x2000000
	s_addc_u32 s19, s17, 0
	s_add_u32 s20, s16, 0x4000000
	s_addc_u32 s21, s17, 0
	s_lshl_b32 s94, s30, 12
	s_or_b32 s94, s15, s94
	v_ashrrev_i32_e32 v6, 6, v4
	v_lshlrev_b32_e32 v102, 5, v6
	v_and_b32_e32 v100, 31, v4
	v_add_u32_e32 v0, s31, v102
	v_or_b32_e32 v0, v0, v100
	v_bfe_u32 v101, v4, 5, 1
	v_lshlrev_b32_e32 v0, s77, v0
	v_add_u32_e32 v7, s15, v0
	v_lshlrev_b32_e32 v92, 4, v101
	v_lshl_or_b32 v8, v7, 7, v92
	v_lshl_add_u32 v94, s30, 12, v7
	global_load_dwordx4 v[0:3], v8, s[16:17]
	global_load_dwordx4 v[88:91], v8, s[16:17] offset:32
	global_load_dwordx4 v[84:87], v8, s[16:17] offset:64
	global_load_dwordx4 v[80:83], v8, s[16:17] offset:96
	v_ashrrev_i32_e32 v95, 31, v94
	v_lshl_add_u64 v[8:9], v[94:95], 2, s[40:41]
	global_load_dword v103, v[8:9], off
	v_add_u32_e32 v214, s50, v234
	s_add_i32 s95, s50, 64
	v_add_u32_e32 v215, s95, v234
	s_add_i32 s95, s50, 128
	v_add_u32_e32 v216, s95, v234
	s_add_i32 s95, s50, 192
	v_add_u32_e32 v217, s95, v234
	s_add_i32 s95, s50, 256
	v_add_u32_e32 v218, s95, v234
	s_add_i32 s95, s50, 320
	v_add_u32_e32 v219, s95, v234
	v_add_u32_e32 v220, s50, v4
	v_cmp_gt_u32_e64 s[80:81], s49, v214
	v_cmp_gt_u32_e64 s[82:83], s49, v215
	v_cmp_gt_u32_e64 s[84:85], s49, v216
	v_cmp_gt_u32_e64 s[86:87], s49, v217
	v_cmp_gt_u32_e64 s[88:89], s49, v218
	v_cmp_gt_u32_e64 s[90:91], s49, v219
	v_cmp_gt_u32_e64 s[92:93], s49, v220
	v_cmp_gt_i32_e32 vcc, s42, v4
	v_cndmask_b32_e64 v214, 0, v214, s[80:81]
	v_cndmask_b32_e64 v215, 0, v215, s[82:83]
	v_cndmask_b32_e64 v216, 0, v216, s[84:85]
	v_cndmask_b32_e64 v217, 0, v217, s[86:87]
	v_cndmask_b32_e64 v218, 0, v218, s[88:89]
	v_cndmask_b32_e64 v219, 0, v219, s[90:91]
	s_and_b64 s[92:93], s[92:93], vcc
	v_lshlrev_b32_e32 v214, s77, v214
	v_lshlrev_b32_e32 v215, s77, v215
	v_lshlrev_b32_e32 v216, s77, v216
	v_lshlrev_b32_e32 v217, s77, v217
	v_lshlrev_b32_e32 v218, s77, v218
	v_lshlrev_b32_e32 v219, s77, v219
	v_cndmask_b32_e64 v220, 0, v220, s[92:93]
	v_add_u32_e32 v214, s15, v214
	v_add_u32_e32 v215, s15, v215
	v_add_u32_e32 v216, s15, v216
	v_add_u32_e32 v217, s15, v217
	v_add_u32_e32 v218, s15, v218
	v_add_u32_e32 v219, s15, v219
	v_lshlrev_b32_e32 v220, s77, v220
	v_lshl_or_b32 v214, v214, 7, v235
	v_lshl_or_b32 v215, v215, 7, v235
	v_lshl_or_b32 v216, v216, 7, v235
	v_lshl_or_b32 v217, v217, 7, v235
	v_lshl_or_b32 v218, v218, 7, v235
	v_lshl_or_b32 v219, v219, 7, v235
	v_add_lshl_u32 v220, v220, s94, 2
	global_load_dwordx4 v[164:167], v214, s[18:19]
	global_load_dwordx4 v[168:171], v214, s[20:21]
	global_load_dwordx4 v[172:175], v215, s[18:19]
	global_load_dwordx4 v[176:179], v215, s[20:21]
	global_load_dwordx4 v[180:183], v216, s[18:19]
	global_load_dwordx4 v[184:187], v216, s[20:21]
	global_load_dwordx4 v[188:191], v217, s[18:19]
	global_load_dwordx4 v[192:195], v217, s[20:21]
	global_load_dwordx4 v[196:199], v218, s[18:19]
	global_load_dwordx4 v[200:203], v218, s[20:21]
	global_load_dwordx4 v[204:207], v219, s[18:19]
	global_load_dwordx4 v[208:211], v219, s[20:21]
	global_load_dword v213, v220, s[40:41]
	s_waitcnt vmcnt(11)
	ds_write_b128 v222, v[164:167]
	ds_write_b128 v223, v[168:171]
	s_waitcnt vmcnt(9)
	ds_write_b128 v222, v[172:175] offset:8192
	ds_write_b128 v223, v[176:179] offset:8192
	s_waitcnt vmcnt(7)
	ds_write_b128 v222, v[180:183] offset:16384
	ds_write_b128 v223, v[184:187] offset:16384
	s_waitcnt vmcnt(5)
	ds_write_b128 v222, v[188:191] offset:24576
	ds_write_b128 v223, v[192:195] offset:24576
	s_waitcnt vmcnt(3)
	ds_write_b128 v222, v[196:199] offset:32768
	ds_write_b128 v223, v[200:203] offset:32768
	s_waitcnt vmcnt(1)
	ds_write_b128 v222, v[204:207] offset:40960
	ds_write_b128 v223, v[208:211] offset:40960
	s_waitcnt vmcnt(0)
	v_cmp_gt_i32_e32 vcc, s42, v4
	v_cvt_f32_i32_e32 v213, v213
	v_mov_b32_e32 v5, 0x4d8f0d18
	v_cndmask_b32_e64 v5, v5, v213, s[92:93]
	s_and_saveexec_b64 s[2:3], vcc
	v_lshl_add_u32 v7, v4, 2, 0
	v_add_u32_e32 v7, 0x18000, v7
	ds_write_b32 v7, v5
	s_or_b64 exec, exec, s[2:3]
	v_lshlrev_b32_e32 v5, 3, v4
	v_lshlrev_b32_e32 v99, 12, v6
	v_bitop3_b32 v7, v92, v5, s39 bitop3:0x78
	v_lshl_or_b32 v14, v100, 7, v99
	v_add3_u32 v15, 0, v7, v14
	s_waitcnt lgkmcnt(0)
	s_barrier
; #define SBAR() __builtin_amdgcn_sched_barrier(0)
; DI void unit(const bf16* __restrict__ QKV, const int* __restrict__ pos, bf16* __restrict__ OA, float* __restrict__ LSE,
;              int b, int h, int d, int r, int qb, float slope, char* lds) {
;     ...
;   f32x16 p[5];
; #pragma unroll
;   for (int ta = 0; ta < 5; ++ta) { p[ta] = f32x16{};
; #pragma unroll
;     for (int d0 = 0; d0 < 4; ++d0) { const bf16x8 a = *(const bf16x8*)(K_lds + PSWZ(wid * 32 + ta * 32 + r32, (d0 * 16 + hi * 8) * 2));
;       p[ta] = __builtin_amdgcn_mfma_f32_32x32x16_bf16(a, qr[d0], p[ta], 0, 0, 0); }
;     SBAR(); }
;   const float C = 0.125f * 1.4426950408889634f, sl2 = slope * 1.4426950408889634f;
;   const float* pbase = (const float*)posk + wid * 32 + 4 * hi; const float pqf = (float)pq;
;   float mx = -1e30f;
; #pragma unroll
;   for (int ta = 0; ta < 5; ++ta) {
; #pragma unroll
;     for (int g = 0; g < 4; ++g) { const f32x4 pk4 = *(const f32x4*)(pbase + ta * 32 + 8 * g);
; #pragma unroll
;       for (int j = 0; j < 4; ++j) { const int rr = 4 * g + j, kr = j + 8 * g + 4 * hi;
;         float sc = fmaf(__builtin_fabsf(pqf - pk4[j]), -sl2, p[ta][rr] * C);
;         if (ta == 0) sc = (kr >= r32) ? sc : -1e30f;
;         if (ta == 4) sc = (kr <= r32) ? sc : -1e30f;
;         p[ta][rr] = sc; mx = fmaxf(mx, sc); } }
	ds_read_b128 v[6:9], v15
	v_and_b32_e32 v5, 0x70, v5
	v_bitop3_b32 v10, v92, v5, 32 bitop3:0x36
	v_add3_u32 v104, 0, v10, v14
	ds_read_b128 v[10:13], v104
	s_waitcnt vmcnt(4) lgkmcnt(1)
	v_mfma_f32_32x32x16_bf16 v[64:79], v[6:9], v[0:3], 0
	v_bitop3_b32 v6, v92, v5, 64 bitop3:0x36
	v_add3_u32 v108, 0, v6, v14
	ds_read_b128 v[6:9], v108
	v_bitop3_b32 v5, v92, v5, s44 bitop3:0x36
	v_add3_u32 v109, 0, v5, v14
	s_add_i32 s2, s48, 1
	v_cvt_f32_ubyte0_e32 v16, s2
	s_waitcnt vmcnt(3) lgkmcnt(1)
	v_mfma_f32_32x32x16_bf16 v[64:79], v[10:13], v[88:91], v[64:79]
	ds_read_b128 v[10:13], v109
	v_cmp_lt_f32_e32 vcc, s43, v16
	s_and_b64 s[2:3], vcc, exec
	s_cselect_b32 s2, 0xffffffc0, 0
	v_cndmask_b32_e32 v17, 0, v96, vcc
	v_sub_f32_e32 v5, v17, v16
	v_exp_f32_e32 v5, v5
	s_waitcnt vmcnt(2) lgkmcnt(1)
	v_mfma_f32_32x32x16_bf16 v[64:79], v[6:9], v[84:87], v[64:79]
	s_ashr_i32 s15, s14, 31
	v_and_b32_e32 v98, 63, v4
	v_ldexp_f32 v110, v5, s2
	s_waitcnt vmcnt(1) lgkmcnt(0)
	v_mfma_f32_32x32x16_bf16 v[64:79], v[10:13], v[80:83], v[64:79]
	ds_read_b128 v[4:7], v15 offset:4096
	ds_read_b128 v[8:11], v104 offset:4096
	s_waitcnt lgkmcnt(1)
	v_mfma_f32_32x32x16_bf16 v[48:63], v[4:7], v[0:3], 0
	s_waitcnt lgkmcnt(0)
	v_mfma_f32_32x32x16_bf16 v[48:63], v[8:11], v[88:91], v[48:63]
	ds_read_b128 v[4:7], v108 offset:4096
	ds_read_b128 v[8:11], v109 offset:4096
	s_waitcnt lgkmcnt(1)
	v_mfma_f32_32x32x16_bf16 v[48:63], v[4:7], v[84:87], v[48:63]
	s_waitcnt lgkmcnt(0)
	v_mfma_f32_32x32x16_bf16 v[48:63], v[8:11], v[80:83], v[48:63]
	ds_read_b128 v[4:7], v15 offset:8192
	ds_read_b128 v[8:11], v104 offset:8192
	s_waitcnt lgkmcnt(1)
	v_mfma_f32_32x32x16_bf16 v[32:47], v[4:7], v[0:3], 0
	s_waitcnt lgkmcnt(0)
	v_mfma_f32_32x32x16_bf16 v[32:47], v[8:11], v[88:91], v[32:47]
	ds_read_b128 v[4:7], v108 offset:8192
	ds_read_b128 v[8:11], v109 offset:8192
	s_waitcnt lgkmcnt(1)
	v_mfma_f32_32x32x16_bf16 v[32:47], v[4:7], v[84:87], v[32:47]
	s_waitcnt lgkmcnt(0)
	v_mfma_f32_32x32x16_bf16 v[32:47], v[8:11], v[80:83], v[32:47]
	ds_read_b128 v[4:7], v15 offset:12288
	ds_read_b128 v[8:11], v104 offset:12288
	s_waitcnt lgkmcnt(1)
	v_mfma_f32_32x32x16_bf16 v[16:31], v[4:7], v[0:3], 0
	s_waitcnt lgkmcnt(0)
	v_mfma_f32_32x32x16_bf16 v[16:31], v[8:11], v[88:91], v[16:31]
	ds_read_b128 v[4:7], v108 offset:12288
	ds_read_b128 v[8:11], v109 offset:12288
	s_waitcnt lgkmcnt(1)
	v_mfma_f32_32x32x16_bf16 v[16:31], v[4:7], v[84:87], v[16:31]
	s_waitcnt lgkmcnt(0)
	v_mfma_f32_32x32x16_bf16 v[16:31], v[8:11], v[80:83], v[16:31]
	ds_read_b128 v[4:7], v15 offset:16384
	ds_read_b128 v[104:107], v104 offset:16384
	s_waitcnt lgkmcnt(1)
	v_mfma_f32_32x32x16_bf16 v[0:15], v[4:7], v[0:3], 0
	s_waitcnt lgkmcnt(0)
	v_mfma_f32_32x32x16_bf16 v[0:15], v[104:107], v[88:91], v[0:15]
	ds_read_b128 v[88:91], v108 offset:16384
	ds_read_b128 v[104:107], v109 offset:16384
	s_waitcnt lgkmcnt(1)
	v_mfma_f32_32x32x16_bf16 v[0:15], v[88:91], v[84:87], v[0:15]
	s_waitcnt lgkmcnt(0)
	v_mfma_f32_32x32x16_bf16 v[0:15], v[104:107], v[80:83], v[0:15]
	v_lshlrev_b32_e32 v80, 2, v102
	v_add3_u32 v88, s46, v80, v92
	ds_read_b128 v[80:83], v88
	ds_read_b128 v[84:87], v88 offset:32
	s_waitcnt vmcnt(0)
	v_cvt_f32_i32_e32 v89, v103
	v_lshlrev_b32_e32 v90, 2, v101
	v_mul_f32_e32 v91, 0xc1000000, v110
	v_add_f32_e32 v64, v64, v134
	s_waitcnt lgkmcnt(1)
	v_sub_f32_e32 v80, v89, v80
	v_fma_f32 v80, |v80|, v91, v64
	v_sub_f32_e32 v81, v89, v81
	v_add_f32_e32 v65, v65, v135
	v_fma_f32 v81, |v81|, v91, v65
	v_add_f32_e32 v66, v66, v136
	v_sub_f32_e32 v65, v89, v82
	v_fma_f32 v82, |v65|, v91, v66
	v_add_f32_e32 v66, v67, v137
	v_sub_f32_e32 v65, v89, v83
	v_fma_f32 v83, |v65|, v91, v66
	v_add_f32_e32 v66, v68, v138
	s_waitcnt lgkmcnt(0)
	v_sub_f32_e32 v65, v89, v84
	v_fma_f32 v84, |v65|, v91, v66
	v_add_f32_e32 v66, v69, v139
	v_sub_f32_e32 v65, v89, v85
	v_max3_f32 v64, v80, s45, v81
	v_fma_f32 v85, |v65|, v91, v66
	v_max3_f32 v64, v64, v82, v83
	v_max3_f32 v68, v64, v84, v85
	v_sub_f32_e32 v64, v89, v86
	v_add_f32_e32 v65, v70, v140
	v_fma_f32 v86, |v64|, v91, v65
	v_add_f32_e32 v65, v71, v141
	v_sub_f32_e32 v64, v89, v87
	v_fma_f32 v87, |v64|, v91, v65
	ds_read_b128 v[64:67], v88 offset:64
	v_add_f32_e32 v72, v72, v142
	v_max3_f32 v107, v68, v86, v87
	ds_read_b128 v[68:71], v88 offset:96
	s_waitcnt lgkmcnt(1)
	v_sub_f32_e32 v64, v89, v64
	v_fma_f32 v72, |v64|, v91, v72
	v_sub_f32_e32 v64, v89, v65
	v_add_f32_e32 v65, v73, v143
	v_fma_f32 v73, |v64|, v91, v65
	v_sub_f32_e32 v65, v89, v66
	v_add_f32_e32 v66, v74, v144
	v_max3_f32 v64, v107, v72, v73
	v_fma_f32 v74, |v65|, v91, v66
	v_add_f32_e32 v66, v75, v145
	v_sub_f32_e32 v65, v89, v67
	v_fma_f32 v75, |v65|, v91, v66
	v_add_f32_e32 v66, v76, v148
	s_waitcnt lgkmcnt(0)
	v_sub_f32_e32 v65, v89, v68
	v_fma_f32 v76, |v65|, v91, v66
	v_add_f32_e32 v66, v77, v149
	v_sub_f32_e32 v65, v89, v69
	v_fma_f32 v77, |v65|, v91, v66
	v_add_f32_e32 v66, v78, v150
	v_sub_f32_e32 v65, v89, v70
	v_fma_f32 v78, |v65|, v91, v66
	v_add_f32_e32 v66, v79, v152
	v_max3_f32 v64, v64, v74, v75
	v_sub_f32_e32 v65, v89, v71
	v_fma_f32 v79, |v65|, v91, v66
	v_max3_f32 v64, v64, v76, v77
	s_nop 0
	v_max3_f32 v115, v64, v78, v79
	ds_read_b128 v[64:67], v88 offset:128
	ds_read_b128 v[68:71], v88 offset:160
	s_waitcnt lgkmcnt(1)
	v_sub_f32_e32 v65, v89, v65
	v_fma_f32 v65, |v65|, v91, v49
	v_sub_f32_e32 v49, v89, v66
	v_sub_f32_e32 v64, v89, v64
	v_fma_f32 v66, |v49|, v91, v50
	v_sub_f32_e32 v49, v89, v67
	v_fma_f32 v64, |v64|, v91, v48
	v_fma_f32 v67, |v49|, v91, v51
	s_waitcnt lgkmcnt(0)
; DI void unit(const bf16* __restrict__ QKV, const int* __restrict__ pos, bf16* __restrict__ OA, float* __restrict__ LSE,
;              int b, int h, int d, int r, int qb, float slope, char* lds) {
;     ...
;   for (int ta = 0; ta < 5; ++ta) {
; #pragma unroll
;     for (int g = 0; g < 4; ++g) { const f32x4 pk4 = *(const f32x4*)(pbase + ta * 32 + 8 * g);
; #pragma unroll
;       for (int j = 0; j < 4; ++j) { const int rr = 4 * g + j, kr = j + 8 * g + 4 * hi;
;         float sc = fmaf(__builtin_fabsf(pqf - pk4[j]), -sl2, p[ta][rr] * C);
;         if (ta == 0) sc = (kr >= r32) ? sc : -1e30f;
;         if (ta == 4) sc = (kr <= r32) ? sc : -1e30f;
;         p[ta][rr] = sc; mx = fmaxf(mx, sc); } }
	v_sub_f32_e32 v49, v89, v68
	v_max3_f32 v48, v115, v64, v65
	v_fma_f32 v68, |v49|, v91, v52
	v_sub_f32_e32 v49, v89, v69
	v_max3_f32 v48, v48, v66, v67
	v_fma_f32 v69, |v49|, v91, v53
	v_max3_f32 v52, v48, v68, v69
	v_sub_f32_e32 v48, v89, v70
	v_fma_f32 v70, |v48|, v91, v54
	ds_read_b128 v[48:51], v88 offset:192
	v_sub_f32_e32 v53, v89, v71
	v_fma_f32 v71, |v53|, v91, v55
	v_max3_f32 v115, v52, v70, v71
	ds_read_b128 v[52:55], v88 offset:224
	s_waitcnt lgkmcnt(1)
	v_sub_f32_e32 v48, v89, v48
	v_fma_f32 v56, |v48|, v91, v56
	v_sub_f32_e32 v48, v89, v49
	v_fma_f32 v57, |v48|, v91, v57
	v_sub_f32_e32 v49, v89, v50
	v_fma_f32 v58, |v49|, v91, v58
	v_sub_f32_e32 v49, v89, v51
	v_fma_f32 v59, |v49|, v91, v59
	s_waitcnt lgkmcnt(0)
	v_sub_f32_e32 v49, v89, v52
	v_fma_f32 v60, |v49|, v91, v60
	v_sub_f32_e32 v49, v89, v53
	v_max3_f32 v48, v115, v56, v57
	v_fma_f32 v61, |v49|, v91, v61
	v_sub_f32_e32 v49, v89, v54
	v_max3_f32 v48, v48, v58, v59
	v_fma_f32 v62, |v49|, v91, v62
	v_sub_f32_e32 v49, v89, v55
	v_max3_f32 v48, v48, v60, v61
	v_fma_f32 v63, |v49|, v91, v63
	v_max3_f32 v115, v48, v62, v63
	ds_read_b128 v[48:51], v88 offset:256
	ds_read_b128 v[52:55], v88 offset:288
	s_waitcnt lgkmcnt(1)
	v_sub_f32_e32 v49, v89, v49
	v_fma_f32 v49, |v49|, v91, v33
	v_sub_f32_e32 v33, v89, v50
	v_sub_f32_e32 v48, v89, v48
	v_fma_f32 v50, |v33|, v91, v34
	v_sub_f32_e32 v33, v89, v51
	v_fma_f32 v48, |v48|, v91, v32
	v_fma_f32 v51, |v33|, v91, v35
	s_waitcnt lgkmcnt(0)
	v_sub_f32_e32 v33, v89, v52
	v_max3_f32 v32, v115, v48, v49
	v_fma_f32 v52, |v33|, v91, v36
	v_sub_f32_e32 v33, v89, v53
	v_max3_f32 v32, v32, v50, v51
	v_fma_f32 v53, |v33|, v91, v37
	v_max3_f32 v36, v32, v52, v53
	v_sub_f32_e32 v32, v89, v54
	v_fma_f32 v54, |v32|, v91, v38
	ds_read_b128 v[32:35], v88 offset:320
	v_sub_f32_e32 v37, v89, v55
	v_fma_f32 v55, |v37|, v91, v39
	v_max3_f32 v115, v36, v54, v55
	ds_read_b128 v[36:39], v88 offset:352
	s_waitcnt lgkmcnt(1)
	v_sub_f32_e32 v32, v89, v32
	v_fma_f32 v40, |v32|, v91, v40
	v_sub_f32_e32 v32, v89, v33
	v_fma_f32 v41, |v32|, v91, v41
	v_sub_f32_e32 v33, v89, v34
	v_fma_f32 v42, |v33|, v91, v42
	v_sub_f32_e32 v33, v89, v35
	v_fma_f32 v43, |v33|, v91, v43
	s_waitcnt lgkmcnt(0)
	v_sub_f32_e32 v33, v89, v36
	v_fma_f32 v44, |v33|, v91, v44
	v_sub_f32_e32 v33, v89, v37
	v_max3_f32 v32, v115, v40, v41
	v_fma_f32 v45, |v33|, v91, v45
	v_sub_f32_e32 v33, v89, v38
	v_max3_f32 v32, v32, v42, v43
	v_fma_f32 v46, |v33|, v91, v46
	v_sub_f32_e32 v33, v89, v39
	v_max3_f32 v32, v32, v44, v45
	v_fma_f32 v47, |v33|, v91, v47
	v_max3_f32 v115, v32, v46, v47
	ds_read_b128 v[32:35], v88 offset:384
	ds_read_b128 v[36:39], v88 offset:416
	s_waitcnt lgkmcnt(1)
	v_sub_f32_e32 v33, v89, v33
	v_fma_f32 v33, |v33|, v91, v17
	v_sub_f32_e32 v17, v89, v34
	v_sub_f32_e32 v32, v89, v32
	v_fma_f32 v34, |v17|, v91, v18
	v_sub_f32_e32 v17, v89, v35
	v_fma_f32 v116, |v32|, v91, v16
	v_fma_f32 v35, |v17|, v91, v19
	s_waitcnt lgkmcnt(0)
	v_sub_f32_e32 v17, v89, v36
	v_max3_f32 v16, v115, v116, v33
	v_fma_f32 v36, |v17|, v91, v20
	v_sub_f32_e32 v17, v89, v37
	v_max3_f32 v16, v16, v34, v35
	v_fma_f32 v37, |v17|, v91, v21
	v_max3_f32 v20, v16, v36, v37
	v_sub_f32_e32 v16, v89, v38
	v_fma_f32 v38, |v16|, v91, v22
	ds_read_b128 v[16:19], v88 offset:448
	v_sub_f32_e32 v21, v89, v39
	v_fma_f32 v39, |v21|, v91, v23
	v_max3_f32 v32, v20, v38, v39
	ds_read_b128 v[20:23], v88 offset:480
	s_waitcnt lgkmcnt(1)
	v_sub_f32_e32 v16, v89, v16
	v_fma_f32 v24, |v16|, v91, v24
	v_sub_f32_e32 v16, v89, v17
	v_fma_f32 v25, |v16|, v91, v25
	v_sub_f32_e32 v17, v89, v18
	v_fma_f32 v26, |v17|, v91, v26
	v_sub_f32_e32 v17, v89, v19
	v_fma_f32 v27, |v17|, v91, v27
	s_waitcnt lgkmcnt(0)
	v_sub_f32_e32 v17, v89, v20
	v_fma_f32 v28, |v17|, v91, v28
	v_sub_f32_e32 v17, v89, v21
	v_max3_f32 v16, v32, v24, v25
	v_fma_f32 v29, |v17|, v91, v29
	v_sub_f32_e32 v17, v89, v22
	v_max3_f32 v16, v16, v26, v27
	v_fma_f32 v30, |v17|, v91, v30
	v_sub_f32_e32 v17, v89, v23
	v_max3_f32 v16, v16, v28, v29
	v_fma_f32 v31, |v17|, v91, v31
	v_max3_f32 v32, v16, v30, v31
	ds_read_b128 v[16:19], v88 offset:512
	ds_read_b128 v[20:23], v88 offset:544
	v_add_f32_e32 v0, v0, v153
	v_add_f32_e32 v2, v2, v155
	s_waitcnt lgkmcnt(1)
	v_sub_f32_e32 v16, v89, v16
	v_fma_f32 v16, |v16|, v91, v0
	v_sub_f32_e32 v17, v89, v17
	v_add_f32_e32 v0, v1, v154
	v_fma_f32 v17, |v17|, v91, v0
	v_sub_f32_e32 v1, v89, v18
	v_fma_f32 v18, |v1|, v91, v2
	v_add_f32_e32 v2, v3, v156
	v_max3_f32 v0, v32, v16, v17
	v_sub_f32_e32 v1, v89, v19
	v_fma_f32 v19, |v1|, v91, v2
	v_add_f32_e32 v2, v4, v157
	v_add_f32_e32 v8, v8, v163
	s_waitcnt lgkmcnt(0)
	v_sub_f32_e32 v1, v89, v20
	v_fma_f32 v20, |v1|, v91, v2
	v_add_f32_e32 v2, v5, v158
	v_max3_f32 v0, v0, v18, v19
	v_sub_f32_e32 v1, v89, v21
	v_fma_f32 v21, |v1|, v91, v2
	s_nop 1
	v_max3_f32 v4, v0, v20, v21
	v_sub_f32_e32 v0, v89, v22
	v_add_f32_e32 v1, v6, v159
	v_fma_f32 v22, |v0|, v91, v1
	v_add_f32_e32 v1, v7, v162
	s_nop 0
	v_sub_f32_e32 v0, v89, v23
	v_fma_f32 v23, |v0|, v91, v1
	ds_read_b128 v[0:3], v88 offset:576
	s_nop 1
	v_max3_f32 v32, v4, v22, v23
	ds_read_b128 v[4:7], v88 offset:608
	s_waitcnt lgkmcnt(1)
	v_sub_f32_e32 v0, v89, v0
	v_fma_f32 v0, |v0|, v91, v8
	v_sub_f32_e32 v1, v89, v1
	v_add_f32_e32 v8, v9, v212
	v_fma_f32 v1, |v1|, v91, v8
	v_sub_f32_e32 v2, v89, v2
	v_add_f32_e32 v9, v10, v228
	v_fma_f32 v2, |v2|, v91, v9
	v_sub_f32_e32 v3, v89, v3
	v_add_f32_e32 v9, v11, v229
	v_fma_f32 v3, |v3|, v91, v9
	s_waitcnt lgkmcnt(0)
; #define SBAR() __builtin_amdgcn_sched_barrier(0)
; DI void unit(const bf16* __restrict__ QKV, const int* __restrict__ pos, bf16* __restrict__ OA, float* __restrict__ LSE,
;              int b, int h, int d, int r, int qb, float slope, char* lds) {
;     ...
;   for (int ta = 0; ta < 5; ++ta) {
; #pragma unroll
;     for (int g = 0; g < 4; ++g) { const f32x4 pk4 = *(const f32x4*)(pbase + ta * 32 + 8 * g);
; #pragma unroll
;       for (int j = 0; j < 4; ++j) { const int rr = 4 * g + j, kr = j + 8 * g + 4 * hi;
;         float sc = fmaf(__builtin_fabsf(pqf - pk4[j]), -sl2, p[ta][rr] * C);
;         if (ta == 0) sc = (kr >= r32) ? sc : -1e30f;
;         if (ta == 4) sc = (kr <= r32) ? sc : -1e30f;
;         p[ta][rr] = sc; mx = fmaxf(mx, sc); } }
;     SBAR(); }
;   { auto x = __builtin_amdgcn_permlane32_swap(__float_as_uint(mx), __float_as_uint(mx), false, false); mx = fmaxf(__uint_as_float(x[0]), __uint_as_float(x[1])); }
;   float ls = 0.f;
; #pragma unroll
;   for (int ta = 0; ta < 5; ++ta)
; #pragma unroll
;     for (int rr = 0; rr < 16; ++rr) { p[ta][rr] = __builtin_amdgcn_exp2f(p[ta][rr] - mx); ls += p[ta][rr]; if (rr == 15) SBAR(); }
;   { auto x = __builtin_amdgcn_permlane32_swap(__float_as_uint(ls), __float_as_uint(ls), false, false); ls = __uint_as_float(x[0]) + __uint_as_float(x[1]); }
	v_sub_f32_e32 v4, v89, v4
	v_add_f32_e32 v9, v12, v230
	v_fma_f32 v4, |v4|, v91, v9
	v_sub_f32_e32 v5, v89, v5
	v_add_f32_e32 v9, v13, v231
	v_fma_f32 v5, |v5|, v91, v9
	v_sub_f32_e32 v6, v89, v6
	v_add_f32_e32 v9, v14, v232
	v_max3_f32 v8, v32, v0, v1
	v_fma_f32 v6, |v6|, v91, v9
	v_sub_f32_e32 v7, v89, v7
	v_add_f32_e32 v9, v15, v233
	v_max3_f32 v8, v8, v2, v3
	v_fma_f32 v7, |v7|, v91, v9
	v_max3_f32 v8, v8, v4, v5
	s_nop 0
	v_max3_f32 v8, v8, v6, v7
	v_mov_b32_e32 v9, v8
	s_nop 1
	v_permlane32_swap_b32_e32 v8, v9
	v_max_f32_e32 v9, v9, v9
	v_max_f32_e32 v8, v8, v8
	v_max_f32_e32 v32, v8, v9
	v_mul_f32_e32 v32, s76, v32
	v_fma_f32 v8, v80, s76, -v32
	v_exp_f32_e32 v8, v8
	v_fma_f32 v9, v81, s76, -v32
	v_exp_f32_e32 v9, v9
	v_fma_f32 v10, v82, s76, -v32
	v_exp_f32_e32 v10, v10
	v_fma_f32 v11, v83, s76, -v32
	v_exp_f32_e32 v11, v11
	v_fma_f32 v12, v84, s76, -v32
	v_exp_f32_e32 v12, v12
	v_fma_f32 v13, v85, s76, -v32
	v_add_f32_e32 v80, 0, v8
	v_exp_f32_e32 v13, v13
	v_fma_f32 v14, v86, s76, -v32
	v_add_f32_e32 v80, v9, v80
	v_exp_f32_e32 v14, v14
	v_fma_f32 v15, v87, s76, -v32
	v_add_f32_e32 v80, v10, v80
	v_exp_f32_e32 v15, v15
	v_fma_f32 v72, v72, s76, -v32
	v_add_f32_e32 v80, v11, v80
	v_exp_f32_e32 v72, v72
	v_fma_f32 v73, v73, s76, -v32
	v_add_f32_e32 v80, v12, v80
	v_exp_f32_e32 v73, v73
	v_fma_f32 v74, v74, s76, -v32
	v_add_f32_e32 v80, v13, v80
	v_exp_f32_e32 v74, v74
	v_fma_f32 v75, v75, s76, -v32
	v_add_f32_e32 v80, v14, v80
	v_exp_f32_e32 v75, v75
	v_fma_f32 v76, v76, s76, -v32
	v_add_f32_e32 v80, v15, v80
	v_exp_f32_e32 v76, v76
	v_fma_f32 v77, v77, s76, -v32
	v_add_f32_e32 v80, v72, v80
	v_exp_f32_e32 v77, v77
	v_fma_f32 v78, v78, s76, -v32
	v_add_f32_e32 v80, v73, v80
	v_exp_f32_e32 v78, v78
	v_add_f32_e32 v80, v74, v80
	v_fma_f32 v79, v79, s76, -v32
	v_add_f32_e32 v80, v75, v80
	v_exp_f32_e32 v79, v79
	v_add_f32_e32 v80, v76, v80
	v_add_f32_e32 v80, v77, v80
	v_add_f32_e32 v80, v78, v80
	v_add_f32_e32 v80, v79, v80
	v_fma_f32 v64, v64, s76, -v32
	v_exp_f32_e32 v64, v64
	v_fma_f32 v65, v65, s76, -v32
	v_exp_f32_e32 v65, v65
	v_fma_f32 v66, v66, s76, -v32
	v_exp_f32_e32 v66, v66
	v_fma_f32 v67, v67, s76, -v32
	v_exp_f32_e32 v67, v67
	v_fma_f32 v68, v68, s76, -v32
	v_exp_f32_e32 v68, v68
	v_fma_f32 v69, v69, s76, -v32
	v_add_f32_e32 v80, v64, v80
	v_exp_f32_e32 v69, v69
	v_fma_f32 v70, v70, s76, -v32
	v_add_f32_e32 v80, v65, v80
	v_exp_f32_e32 v70, v70
	v_fma_f32 v71, v71, s76, -v32
	v_add_f32_e32 v80, v66, v80
	v_exp_f32_e32 v71, v71
	v_fma_f32 v56, v56, s76, -v32
	v_add_f32_e32 v80, v67, v80
	v_exp_f32_e32 v56, v56
	v_fma_f32 v57, v57, s76, -v32
	v_add_f32_e32 v80, v68, v80
	v_exp_f32_e32 v57, v57
	v_fma_f32 v58, v58, s76, -v32
	v_add_f32_e32 v80, v69, v80
	v_exp_f32_e32 v58, v58
	v_fma_f32 v59, v59, s76, -v32
	v_add_f32_e32 v80, v70, v80
	v_exp_f32_e32 v59, v59
	v_fma_f32 v60, v60, s76, -v32
	v_add_f32_e32 v80, v71, v80
	v_exp_f32_e32 v60, v60
	v_fma_f32 v61, v61, s76, -v32
	v_add_f32_e32 v80, v56, v80
	v_exp_f32_e32 v61, v61
	v_fma_f32 v62, v62, s76, -v32
	v_add_f32_e32 v80, v57, v80
	v_exp_f32_e32 v62, v62
	v_add_f32_e32 v80, v58, v80
	v_fma_f32 v63, v63, s76, -v32
	v_add_f32_e32 v80, v59, v80
	v_exp_f32_e32 v63, v63
	v_add_f32_e32 v80, v60, v80
	v_add_f32_e32 v80, v61, v80
	v_add_f32_e32 v80, v62, v80
	v_add_f32_e32 v80, v63, v80
	v_fma_f32 v40, v40, s76, -v32
	v_exp_f32_e32 v87, v40
	v_fma_f32 v40, v41, s76, -v32
	v_fma_f32 v48, v48, s76, -v32
	v_exp_f32_e32 v88, v40
	v_fma_f32 v40, v42, s76, -v32
	v_exp_f32_e32 v81, v48
	v_fma_f32 v48, v49, s76, -v32
	v_exp_f32_e32 v89, v40
	v_fma_f32 v40, v43, s76, -v32
	v_exp_f32_e32 v82, v48
	v_fma_f32 v48, v50, s76, -v32
	v_exp_f32_e32 v90, v40
	v_fma_f32 v40, v44, s76, -v32
	v_exp_f32_e32 v83, v48
	v_fma_f32 v48, v51, s76, -v32
	v_exp_f32_e32 v91, v40
	v_fma_f32 v40, v45, s76, -v32
	v_exp_f32_e32 v84, v48
	v_fma_f32 v48, v52, s76, -v32
	v_exp_f32_e32 v100, v40
	v_fma_f32 v40, v46, s76, -v32
	v_exp_f32_e32 v85, v48
	v_fma_f32 v48, v53, s76, -v32
	v_exp_f32_e32 v101, v40
	v_add_f32_e32 v40, v81, v80
	v_exp_f32_e32 v86, v48
	v_fma_f32 v48, v54, s76, -v32
	v_add_f32_e32 v40, v82, v40
	v_exp_f32_e32 v54, v48
	v_fma_f32 v48, v55, s76, -v32
	v_add_f32_e32 v40, v83, v40
	v_exp_f32_e32 v55, v48
	v_add_f32_e32 v40, v84, v40
	v_add_f32_e32 v40, v85, v40
	v_add_f32_e32 v40, v86, v40
	v_add_f32_e32 v40, v54, v40
	v_add_f32_e32 v40, v55, v40
	v_add_f32_e32 v40, v87, v40
	v_add_f32_e32 v40, v88, v40
	v_add_f32_e32 v40, v89, v40
	v_fma_f32 v41, v47, s76, -v32
	v_add_f32_e32 v40, v90, v40
	v_exp_f32_e32 v80, v41
	v_add_f32_e32 v40, v91, v40
	v_add_f32_e32 v40, v100, v40
	v_add_f32_e32 v40, v101, v40
	v_add_f32_e32 v40, v80, v40
	v_fma_f32 v24, v24, s76, -v32
	v_exp_f32_e32 v109, v24
	v_fma_f32 v24, v25, s76, -v32
	v_fma_f32 v41, v116, s76, -v32
	v_exp_f32_e32 v110, v24
	v_fma_f32 v24, v26, s76, -v32
	v_exp_f32_e32 v102, v41
	v_fma_f32 v33, v33, s76, -v32
	v_exp_f32_e32 v111, v24
	v_fma_f32 v24, v27, s76, -v32
	v_exp_f32_e32 v33, v33
	v_fma_f32 v34, v34, s76, -v32
	v_exp_f32_e32 v112, v24
	v_fma_f32 v24, v28, s76, -v32
	v_exp_f32_e32 v103, v34
	v_fma_f32 v34, v35, s76, -v32
	v_exp_f32_e32 v113, v24
	v_fma_f32 v24, v29, s76, -v32
	v_exp_f32_e32 v104, v34
	v_fma_f32 v34, v36, s76, -v32
	v_exp_f32_e32 v114, v24
	v_fma_f32 v24, v30, s76, -v32
	v_exp_f32_e32 v105, v34
	v_fma_f32 v34, v37, s76, -v32
	v_exp_f32_e32 v115, v24
	v_add_f32_e32 v24, v102, v40
	v_exp_f32_e32 v106, v34
	v_fma_f32 v34, v38, s76, -v32
	v_add_f32_e32 v24, v33, v24
	v_exp_f32_e32 v107, v34
	v_fma_f32 v34, v39, s76, -v32
	v_add_f32_e32 v24, v103, v24
	v_exp_f32_e32 v108, v34
	v_add_f32_e32 v24, v104, v24
	v_add_f32_e32 v24, v105, v24
; #define SBAR() __builtin_amdgcn_sched_barrier(0)
; DI int v_rd_base(int lane) { return ((lane & 3) << 3) | (((lane >> 2) & 3) << 6) | (((lane >> 4) & 1) << 5) | (((lane >> 5) & 1) << 8); }
; DI s16x4 vtr(const char* p) { return __builtin_bit_cast(s16x4, __builtin_amdgcn_ds_read_tr16_b64_v4i16((LAS v4i16_t*)(uintptr_t)p)); }
; DI void unit(const bf16* __restrict__ QKV, const int* __restrict__ pos, bf16* __restrict__ OA, float* __restrict__ LSE,
;              int b, int h, int d, int r, int qb, float slope, char* lds) {
;     ...
;     for (int rr = 0; rr < 16; ++rr) { p[ta][rr] = __builtin_amdgcn_exp2f(p[ta][rr] - mx); ls += p[ta][rr]; if (rr == 15) SBAR(); }
;   { auto x = __builtin_amdgcn_permlane32_swap(__float_as_uint(ls), __float_as_uint(ls), false, false); ls = __uint_as_float(x[0]) + __uint_as_float(x[1]); }
;   f32x16 o[2] = {};
;   const char* vb = V_lds + att::v_rd_base(lane) + wid * 2 * 2048;
; #pragma unroll
;   for (int ta = 0; ta < 5; ++ta) {
;     bf16x8 pa0, pa1; PK4(p[ta], 0, pa0); PK4(p[ta], 8, pa1);
; #pragma unroll
;     for (int d0 = 0; d0 < 2; ++d0) {
;       const s16x4 l0 = vtr(vb + (2 * ta) * 2048 + d0 * 512), h0 = vtr(vb + (2 * ta) * 2048 + 1024 + d0 * 512);
;       const s16x4 l1 = vtr(vb + (2 * ta + 1) * 2048 + d0 * 512), h1 = vtr(vb + (2 * ta + 1) * 2048 + 1024 + d0 * 512);
;       o[d0] = __builtin_amdgcn_mfma_f32_32x32x16_bf16((bf16x8){l0[0], l0[1], l0[2], l0[3], h0[0], h0[1], h0[2], h0[3]}, pa0, o[d0], 0, 0, 0);
;       o[d0] = __builtin_amdgcn_mfma_f32_32x32x16_bf16((bf16x8){l1[0], l1[1], l1[2], l1[3], h1[0], h1[1], h1[2], h1[3]}, pa1, o[d0], 0, 0, 0);
	v_add_f32_e32 v24, v106, v24
	v_add_f32_e32 v24, v107, v24
	v_add_f32_e32 v24, v108, v24
	v_add_f32_e32 v24, v109, v24
	v_add_f32_e32 v24, v110, v24
	v_add_f32_e32 v24, v111, v24
	v_fma_f32 v25, v31, s76, -v32
	v_add_f32_e32 v24, v112, v24
	v_exp_f32_e32 v116, v25
	v_add_f32_e32 v24, v113, v24
	v_add_f32_e32 v24, v114, v24
	v_add_f32_e32 v24, v115, v24
	v_add_f32_e32 v24, v116, v24
	v_fma_f32 v0, v0, s76, -v32
	v_exp_f32_e32 v125, v0
	v_fma_f32 v0, v1, s76, -v32
	v_fma_f32 v16, v16, s76, -v32
	v_exp_f32_e32 v126, v0
	v_fma_f32 v0, v2, s76, -v32
	v_exp_f32_e32 v117, v16
	v_fma_f32 v16, v17, s76, -v32
	v_exp_f32_e32 v127, v0
	v_fma_f32 v0, v3, s76, -v32
	v_exp_f32_e32 v118, v16
	v_fma_f32 v16, v18, s76, -v32
	v_exp_f32_e32 v128, v0
	v_fma_f32 v0, v4, s76, -v32
	v_exp_f32_e32 v119, v16
	v_fma_f32 v16, v19, s76, -v32
	v_exp_f32_e32 v129, v0
	v_fma_f32 v0, v5, s76, -v32
	v_exp_f32_e32 v120, v16
	v_fma_f32 v16, v20, s76, -v32
	v_exp_f32_e32 v130, v0
	v_fma_f32 v0, v6, s76, -v32
	v_exp_f32_e32 v121, v16
	v_fma_f32 v16, v21, s76, -v32
	v_exp_f32_e32 v131, v0
	v_add_f32_e32 v0, v117, v24
	v_exp_f32_e32 v122, v16
	v_fma_f32 v16, v22, s76, -v32
	v_add_f32_e32 v0, v118, v0
	v_exp_f32_e32 v123, v16
	v_fma_f32 v16, v23, s76, -v32
	v_add_f32_e32 v0, v119, v0
	v_exp_f32_e32 v124, v16
	v_add_f32_e32 v0, v120, v0
	v_add_f32_e32 v0, v121, v0
	v_add_f32_e32 v0, v122, v0
	v_add_f32_e32 v0, v123, v0
	v_add_f32_e32 v0, v124, v0
	v_add_f32_e32 v0, v125, v0
	v_add_f32_e32 v0, v126, v0
	v_add_f32_e32 v0, v127, v0
	v_fma_f32 v1, v7, s76, -v32
	v_add_f32_e32 v0, v128, v0
	v_exp_f32_e32 v132, v1
	v_add_f32_e32 v0, v129, v0
	v_add_f32_e32 v0, v130, v0
	v_add_f32_e32 v0, v131, v0
	v_add_f32_e32 v133, v132, v0
	v_lshlrev_b32_e32 v0, 3, v98
	v_and_b32_e32 v1, 24, v0
	v_lshlrev_b32_e32 v2, 4, v98
	v_lshlrev_b32_e32 v3, 1, v98
	v_and_b32_e32 v2, 0xc0, v2
	v_and_b32_e32 v3, 32, v3
	v_add_u32_e32 v1, 0, v1
	v_and_b32_e32 v0, 0x100, v0
	v_add3_u32 v1, v1, v2, v3
	v_add3_u32 v99, v1, v0, v99
	v_cvt_pk_bf16_f32 v0, v8, v9
	v_cvt_pk_bf16_f32 v1, v10, v11
	v_cvt_pk_bf16_f32 v2, v12, v13
	v_cvt_pk_bf16_f32 v3, v14, v15
	v_cvt_pk_bf16_f32 v34, v72, v73
	v_cvt_pk_bf16_f32 v35, v74, v75
	v_cvt_pk_bf16_f32 v36, v76, v77
	v_cvt_pk_bf16_f32 v37, v78, v79
	ds_read_b64_tr_b16 v[4:5], v99 offset:49152
	ds_read_b64_tr_b16 v[6:7], v99 offset:50176
	v_permlane32_swap_b32_e32 v0, v2
	v_permlane32_swap_b32_e32 v1, v3
	ds_read_b64_tr_b16 v[10:11], v99 offset:50688
	ds_read_b64_tr_b16 v[8:9], v99 offset:49664
	s_waitcnt lgkmcnt(2)
	v_mfma_f32_32x32x16_bf16 v[16:31], v[4:7], v[0:3], 0
	ds_read_b64_tr_b16 v[4:5], v99 offset:51200
	ds_read_b64_tr_b16 v[6:7], v99 offset:52224
	v_permlane32_swap_b32_e32 v34, v36
	v_permlane32_swap_b32_e32 v35, v37
	ds_read_b64_tr_b16 v[40:41], v99 offset:52736
	ds_read_b64_tr_b16 v[38:39], v99 offset:51712
	v_mov_b32_e32 v72, v133
	s_waitcnt lgkmcnt(2)
	v_mfma_f32_32x32x16_bf16 v[16:31], v[4:7], v[34:37], v[16:31]
	v_permlane32_swap_b32_e32 v133, v72
	v_add_u32_e32 v73, 0xc000, v99
	v_mfma_f32_32x32x16_bf16 v[0:15], v[8:11], v[0:3], 0
	s_waitcnt lgkmcnt(0)
	v_mfma_f32_32x32x16_bf16 v[0:15], v[38:41], v[34:37], v[0:15]
	v_cvt_pk_bf16_f32 v34, v64, v65
	v_cvt_pk_bf16_f32 v35, v66, v67
	v_cvt_pk_bf16_f32 v36, v68, v69
	v_cvt_pk_bf16_f32 v37, v70, v71
	v_cvt_pk_bf16_f32 v38, v56, v57
	v_cvt_pk_bf16_f32 v39, v58, v59
	v_cvt_pk_bf16_f32 v40, v60, v61
	v_cvt_pk_bf16_f32 v41, v62, v63
	ds_read_b64_tr_b16 v[42:43], v99 offset:53248
	ds_read_b64_tr_b16 v[44:45], v99 offset:54272
	ds_read_b64_tr_b16 v[48:49], v99 offset:54784
	ds_read_b64_tr_b16 v[46:47], v99 offset:53760
	v_permlane32_swap_b32_e32 v34, v36
	v_permlane32_swap_b32_e32 v35, v37
	v_permlane32_swap_b32_e32 v38, v40
	s_waitcnt lgkmcnt(2)
	v_mfma_f32_32x32x16_bf16 v[16:31], v[42:45], v[34:37], v[16:31]
	ds_read_b64_tr_b16 v[42:43], v99 offset:55296
	ds_read_b64_tr_b16 v[44:45], v99 offset:56320
	ds_read_b64_tr_b16 v[52:53], v99 offset:56832
	ds_read_b64_tr_b16 v[50:51], v99 offset:55808
	v_permlane32_swap_b32_e32 v39, v41
	s_waitcnt lgkmcnt(4)
	v_mfma_f32_32x32x16_bf16 v[0:15], v[46:49], v[34:37], v[0:15]
	s_waitcnt lgkmcnt(2)
; #define SBAR() __builtin_amdgcn_sched_barrier(0)
; DI s16x4 vtr(const char* p) { return __builtin_bit_cast(s16x4, __builtin_amdgcn_ds_read_tr16_b64_v4i16((LAS v4i16_t*)(uintptr_t)p)); }
; DI void unit(const bf16* __restrict__ QKV, const int* __restrict__ pos, bf16* __restrict__ OA, float* __restrict__ LSE,
;              int b, int h, int d, int r, int qb, float slope, char* lds) {
;     ...
;   for (int ta = 0; ta < 5; ++ta) {
;     bf16x8 pa0, pa1; PK4(p[ta], 0, pa0); PK4(p[ta], 8, pa1);
; #pragma unroll
;     for (int d0 = 0; d0 < 2; ++d0) {
;       const s16x4 l0 = vtr(vb + (2 * ta) * 2048 + d0 * 512), h0 = vtr(vb + (2 * ta) * 2048 + 1024 + d0 * 512);
;       const s16x4 l1 = vtr(vb + (2 * ta + 1) * 2048 + d0 * 512), h1 = vtr(vb + (2 * ta + 1) * 2048 + 1024 + d0 * 512);
;       o[d0] = __builtin_amdgcn_mfma_f32_32x32x16_bf16((bf16x8){l0[0], l0[1], l0[2], l0[3], h0[0], h0[1], h0[2], h0[3]}, pa0, o[d0], 0, 0, 0);
;       o[d0] = __builtin_amdgcn_mfma_f32_32x32x16_bf16((bf16x8){l1[0], l1[1], l1[2], l1[3], h1[0], h1[1], h1[2], h1[3]}, pa1, o[d0], 0, 0, 0);
;     }
;     SBAR();
;   }
;   if (hi == 0) LSE[(size_t)(b * SEQ + tq) * 8 + h] = (mx + __builtin_amdgcn_logf(ls)) * 0.6931471805599453f;
	v_mfma_f32_32x32x16_bf16 v[16:31], v[42:45], v[38:41], v[16:31]
	s_waitcnt lgkmcnt(0)
	v_mfma_f32_32x32x16_bf16 v[0:15], v[50:53], v[38:41], v[0:15]
	v_cvt_pk_bf16_f32 v34, v81, v82
	v_cvt_pk_bf16_f32 v35, v83, v84
	v_cvt_pk_bf16_f32 v36, v85, v86
	v_cvt_pk_bf16_f32 v37, v54, v55
	v_cvt_pk_bf16_f32 v38, v87, v88
	v_cvt_pk_bf16_f32 v39, v89, v90
	v_cvt_pk_bf16_f32 v40, v91, v100
	v_cvt_pk_bf16_f32 v41, v101, v80
	ds_read_b64_tr_b16 v[42:43], v99 offset:57344
	ds_read_b64_tr_b16 v[44:45], v99 offset:58368
	ds_read_b64_tr_b16 v[48:49], v99 offset:58880
	ds_read_b64_tr_b16 v[46:47], v99 offset:57856
	v_permlane32_swap_b32_e32 v34, v36
	v_permlane32_swap_b32_e32 v35, v37
	v_permlane32_swap_b32_e32 v38, v40
	s_waitcnt lgkmcnt(2)
	v_mfma_f32_32x32x16_bf16 v[16:31], v[42:45], v[34:37], v[16:31]
	ds_read_b64_tr_b16 v[42:43], v99 offset:59392
	ds_read_b64_tr_b16 v[44:45], v99 offset:60416
	ds_read_b64_tr_b16 v[52:53], v99 offset:60928
	ds_read_b64_tr_b16 v[50:51], v99 offset:59904
	v_permlane32_swap_b32_e32 v39, v41
	s_waitcnt lgkmcnt(4)
	v_mfma_f32_32x32x16_bf16 v[0:15], v[46:49], v[34:37], v[0:15]
	s_waitcnt lgkmcnt(2)
	v_mfma_f32_32x32x16_bf16 v[16:31], v[42:45], v[38:41], v[16:31]
	s_waitcnt lgkmcnt(0)
	v_mfma_f32_32x32x16_bf16 v[0:15], v[50:53], v[38:41], v[0:15]
	v_cvt_pk_bf16_f32 v34, v102, v33
	v_cvt_pk_bf16_f32 v35, v103, v104
	v_cvt_pk_bf16_f32 v36, v105, v106
	v_cvt_pk_bf16_f32 v37, v107, v108
	v_cvt_pk_bf16_f32 v38, v109, v110
	v_cvt_pk_bf16_f32 v39, v111, v112
	v_cvt_pk_bf16_f32 v40, v113, v114
	v_cvt_pk_bf16_f32 v41, v115, v116
	ds_read_b64_tr_b16 v[42:43], v99 offset:61440
	ds_read_b64_tr_b16 v[44:45], v99 offset:62464
	ds_read_b64_tr_b16 v[48:49], v99 offset:62976
	ds_read_b64_tr_b16 v[46:47], v99 offset:61952
	v_permlane32_swap_b32_e32 v34, v36
	v_permlane32_swap_b32_e32 v35, v37
	v_permlane32_swap_b32_e32 v38, v40
	s_waitcnt lgkmcnt(2)
	v_mfma_f32_32x32x16_bf16 v[16:31], v[42:45], v[34:37], v[16:31]
	ds_read_b64_tr_b16 v[42:43], v99 offset:63488
	ds_read_b64_tr_b16 v[44:45], v99 offset:64512
	ds_read_b64_tr_b16 v[52:53], v99 offset:65024
	ds_read_b64_tr_b16 v[50:51], v99 offset:64000
	v_permlane32_swap_b32_e32 v39, v41
	s_waitcnt lgkmcnt(4)
	v_mfma_f32_32x32x16_bf16 v[0:15], v[46:49], v[34:37], v[0:15]
	s_waitcnt lgkmcnt(2)
	v_mfma_f32_32x32x16_bf16 v[16:31], v[42:45], v[38:41], v[16:31]
	s_waitcnt lgkmcnt(0)
	v_mfma_f32_32x32x16_bf16 v[0:15], v[50:53], v[38:41], v[0:15]
	v_cvt_pk_bf16_f32 v34, v117, v118
	v_cvt_pk_bf16_f32 v35, v119, v120
	v_cvt_pk_bf16_f32 v36, v121, v122
	v_cvt_pk_bf16_f32 v37, v123, v124
	v_cvt_pk_bf16_f32 v38, v125, v126
	v_cvt_pk_bf16_f32 v39, v127, v128
	v_cvt_pk_bf16_f32 v40, v129, v130
	v_cvt_pk_bf16_f32 v41, v131, v132
	ds_read_b64_tr_b16 v[42:43], v73 offset:16384
	ds_read_b64_tr_b16 v[44:45], v73 offset:17408
	ds_read_b64_tr_b16 v[48:49], v73 offset:17920
	ds_read_b64_tr_b16 v[46:47], v73 offset:16896
	v_permlane32_swap_b32_e32 v34, v36
	v_permlane32_swap_b32_e32 v35, v37
	v_permlane32_swap_b32_e32 v38, v40
	s_waitcnt lgkmcnt(2)
	v_mfma_f32_32x32x16_bf16 v[16:31], v[42:45], v[34:37], v[16:31]
	ds_read_b64_tr_b16 v[42:43], v73 offset:18432
	ds_read_b64_tr_b16 v[44:45], v73 offset:19456
	ds_read_b64_tr_b16 v[52:53], v73 offset:19968
	ds_read_b64_tr_b16 v[50:51], v73 offset:18944
	v_permlane32_swap_b32_e32 v39, v41
	s_waitcnt lgkmcnt(4)
	v_mfma_f32_32x32x16_bf16 v[0:15], v[46:49], v[34:37], v[0:15]
	s_waitcnt lgkmcnt(2)
	v_mfma_f32_32x32x16_bf16 v[16:31], v[42:45], v[38:41], v[16:31]
	s_waitcnt lgkmcnt(0)
	v_mfma_f32_32x32x16_bf16 v[0:15], v[50:53], v[38:41], v[0:15]
	v_add_f32_e32 v33, v133, v72
	v_cmp_gt_u32_e32 vcc, 32, v98
	s_and_saveexec_b64 s[2:3], vcc
	s_cbranch_execz .LBB0_857
	v_log_f32_e32 v34, v33
	s_lshl_b64 s[4:5], s[14:15], 20
	s_add_u32 s4, s13, s4
	s_addc_u32 s5, s38, s5
	v_add_f32_e32 v32, v32, v34
	v_lshlrev_b64 v[34:35], 5, v[94:95]
	v_lshl_add_u64 v[34:35], s[4:5], 0, v[34:35]
	s_lshl_b32 s8, s48, 2
	v_mul_f32_e32 v32, 0x3f317218, v32
	v_lshl_add_u64 v[34:35], v[34:35], 0, s[8:9]
	global_store_dword v[34:35], v32, off
	s_branch .LBB0_857
